# idle-tail filling rebalanced: phase 0 transposes only ffn1 gate/up; ffn1-down + w_in + ffn2-down go to the phase-2 tail, ffn2 gate/up to the phase-3 ctx tail, the four small late weights to the phase-
# speedup vs baseline: 1.0122x; 1.0029x over previous
; __device__ __forceinline__ void phase0(const Params& P, unsigned char* smem) {
;     ...
;         for (int base = blockIdx.x * 2; base < total; base += stride) {
;             float v[8];
; #pragma unroll
;             for (int i = 0; i < 8; ++i) v[i] = vn[i];
;             cur = nxt; Nc = Nn;
;             if (base + stride < total) { lookup(it + stride, nxt, Nn); transpose_load(nxt, Nn, vn); }
;             transpose_store(cur, v, scr);
;             it += stride;
;         }
.Ltr_le1:
	s_add_u32 s2, s2, 1
	s_cmp_lt_u32 s2, 1
	s_cbranch_scc1 .Ltr2_common
	s_cmp_lg_u32 s17, 0
	s_cbranch_scc1 .Ltr_last0f
	s_cmp_eq_u32 s2, 1
	s_cbranch_scc0 .Ltr2_stride
	s_add_u32 s1, s18, 0x800
	s_branch .Ltr2_chk

; __device__ __forceinline__ void phase0(const Params& P, unsigned char* smem) {
;     ...
;     auto lookup = [&](int it, TItem& t, int& N) {
;         int r = it < total ? it : total - 1;
;         t.src = nullptr; t.dst = nullptr; t.K = 0; t.mode = 0; t.n0 = 0; N = 0;
; #pragma unroll
;         for (int i = 0; i < 11; ++i) {
;             const int cnt = (tw[i].K >> 6) * (tw[i].N >> 5);
;             if (r >= 0 && r < cnt) {
;                 const int nblk = tw[i].N >> 5, kb = r / nblk, nb = r - kb * nblk, k0 = kb * 64, n0 = nb * 32, tid = threadIdx.x & 255;
;                 N = tw[i].N; t.K = tw[i].K; t.mode = tw[i].mode; t.n0 = n0;
;                 t.src = P.in[tw[i].in] + (size_t)(k0 + (tid >> 5)) * tw[i].N + n0 + (tid & 31);
;                 t.dst = (bf16_t*)(P.ws + tw[i].off) + k0 + (tid & 7) * 8;
;             }
;             r -= cnt;
;         }
;     };
.Ltr2_chk:
	s_cmpk_lt_u32 s1, 0xb00
	s_cbranch_scc0 .Ltr_last0f
	s_add_u32 s19, s1, 0x0
	s_cmpk_lt_u32 s19, 0x580
	s_cbranch_scc1 .Ltr3_m0
	s_cmpk_lt_u32 s19, 0xb00
	s_cbranch_scc1 .Ltr3_m1
	s_cmpk_lt_u32 s19, 0x1080
	s_cbranch_scc1 .Ltr3_m2
	s_cmpk_lt_u32 s19, 0x1600
	s_cbranch_scc1 .Ltr3_m3
	s_cmpk_lt_u32 s19, 0x1b80
	s_cbranch_scc1 .Ltr3_m4
	s_cmpk_lt_u32 s19, 0x2100
	s_cbranch_scc1 .Ltr3_m5
	s_cmpk_lt_u32 s19, 0x2910
	s_cbranch_scc1 .Ltr3_m6
	s_cmpk_lt_u32 s19, 0x2990
	s_cbranch_scc1 .Ltr3_m7
	s_cmpk_lt_u32 s19, 0x2a90
	s_cbranch_scc1 .Ltr3_m8
	s_cmpk_lt_u32 s19, 0x2b90
	s_cbranch_scc1 .Ltr3_m9
	s_sub_u32 s3, s19, 0x2b90
	v_readlane_b32 s6, v251, 43
	v_readlane_b32 s7, v251, 44
	s_mov_b32 s13, 0x2c00000
	s_mov_b32 s14, 0
	s_branch .Ltr3_c1024_1024

; __device__ __forceinline__ void phase0(const Params& P, unsigned char* smem) {
;     ...
;         for (int base = blockIdx.x * 2; base < total; base += stride) {
;             float v[8];
; #pragma unroll
;             for (int i = 0; i < 8; ++i) v[i] = vn[i];
;             cur = nxt; Nc = Nn;
;             if (base + stride < total) { lookup(it + stride, nxt, Nn); transpose_load(nxt, Nn, vn); }
;             transpose_store(cur, v, scr);
;             it += stride;
;         }
.Ltr_pe1:
.Ltr_loop:
	s_add_u32 s2, s2, 1
	s_cmp_lt_u32 s2, 1
	s_cbranch_scc1 .Ltr4_common
	s_cmp_lg_u32 s17, 0
	s_cbranch_scc1 .Ltr_last1
	s_cmp_eq_u32 s2, 1
	s_cbranch_scc0 .Ltr4_stride
	s_add_u32 s1, s18, 0x800
	s_branch .Ltr4_chk

; __device__ __forceinline__ void phase0(const Params& P, unsigned char* smem) {
;     ...
;     auto lookup = [&](int it, TItem& t, int& N) {
;         int r = it < total ? it : total - 1;
;         t.src = nullptr; t.dst = nullptr; t.K = 0; t.mode = 0; t.n0 = 0; N = 0;
; #pragma unroll
;         for (int i = 0; i < 11; ++i) {
;             const int cnt = (tw[i].K >> 6) * (tw[i].N >> 5);
;             if (r >= 0 && r < cnt) {
;                 const int nblk = tw[i].N >> 5, kb = r / nblk, nb = r - kb * nblk, k0 = kb * 64, n0 = nb * 32, tid = threadIdx.x & 255;
;                 N = tw[i].N; t.K = tw[i].K; t.mode = tw[i].mode; t.n0 = n0;
;                 t.src = P.in[tw[i].in] + (size_t)(k0 + (tid >> 5)) * tw[i].N + n0 + (tid & 31);
;                 t.dst = (bf16_t*)(P.ws + tw[i].off) + k0 + (tid & 7) * 8;
;             }
;             r -= cnt;
;         }
;     };
;     {
;         const int stride = gridDim.x * 2;
;         int it = blockIdx.x * 2 + hb;
;         TItem cur, nxt; int Nc = 0, Nn = 0; float vn[8];
;         if (blockIdx.x * 2 < total) { lookup(it, nxt, Nn); transpose_load(nxt, Nn, vn); }
;         for (int base = blockIdx.x * 2; base < total; base += stride) {
;             float v[8];
; #pragma unroll
;             for (int i = 0; i < 8; ++i) v[i] = vn[i];
;             cur = nxt; Nc = Nn;
;             if (base + stride < total) { lookup(it + stride, nxt, Nn); transpose_load(nxt, Nn, vn); }
;             transpose_store(cur, v, scr);
;             it += stride;
;         }
;     }
.LBB0_282:
	s_cmpk_lt_u32 s33, 0x58
	s_cbranch_scc1 .Ltq_skip
	v_and_b32_e32 v1, 63, v168
	v_lshrrev_b32_e32 v14, 6, v168
	s_nop 1
	v_readfirstlane_b32 s0, v14
	s_nop 3
	v_lshrrev_b32_e32 v2, 3, v1
	v_and_b32_e32 v3, 7, v1
	v_lshrrev_b32_e32 v4, 2, v2
	v_and_b32_e32 v14, 3, v2
	v_lshl_or_b32 v4, v4, 3, v14
	s_mulk_i32 s0, 0x2100
	s_add_u32 s3, s0, 16
	v_mul_u32_u24_e32 v5, 0x84, v2
	v_lshl_add_u32 v5, v3, 4, v5
	v_add_u32_e32 v5, s3, v5
	v_add_u32_e32 v6, 0x420, v5
	v_add_u32_e32 v7, 0x420, v6
	v_add_u32_e32 v8, 0x420, v7
	v_add_u32_e32 v9, 0x420, v8
	v_add_u32_e32 v10, 0x420, v9
	v_add_u32_e32 v11, 0x420, v10
	v_add_u32_e32 v12, 0x420, v11
	v_mul_u32_u24_e32 v13, 0x420, v3
	v_lshl_add_u32 v13, v2, 2, v13
	v_add_u32_e32 v13, s3, v13
	v_lshlrev_b32_e32 v3, 4, v3
	v_lshrrev_b32_e32 v14, 6, v168
	s_nop 1
	v_readfirstlane_b32 s0, v14
	s_nop 3
	s_sub_u32 s4, s33, 88
	s_lshl_b32 s4, s4, 3
	s_add_u32 s0, s0, s4
	s_mov_b32 s1, s0
	s_movk_i32 s19, 0x1600
	s_cmpk_lt_u32 s1, 0x580
	s_cselect_b32 s19, 0xb00, s19
	s_add_u32 s19, s19, s1
	s_cmpk_lt_u32 s19, 0x580
	s_cbranch_scc1 .Ltq1_m0
	s_cmpk_lt_u32 s19, 0xb00
	s_cbranch_scc1 .Ltq1_m1
	s_cmpk_lt_u32 s19, 0x1080
	s_cbranch_scc1 .Ltq1_m2
	s_cmpk_lt_u32 s19, 0x1600
	s_cbranch_scc1 .Ltq1_m3
	s_cmpk_lt_u32 s19, 0x1b80
	s_cbranch_scc1 .Ltq1_m4
	s_cmpk_lt_u32 s19, 0x2100
	s_cbranch_scc1 .Ltq1_m5
	s_cmpk_lt_u32 s19, 0x2910
	s_cbranch_scc1 .Ltq1_m6
	s_cmpk_lt_u32 s19, 0x2990
	s_cbranch_scc1 .Ltq1_m7
	s_cmpk_lt_u32 s19, 0x2a90
	s_cbranch_scc1 .Ltq1_m8
	s_cmpk_lt_u32 s19, 0x2b90
	s_cbranch_scc1 .Ltq1_m9
	s_sub_u32 s3, s19, 0x2b90
	v_readlane_b32 s6, v251, 43
	v_readlane_b32 s7, v251, 44
	s_mov_b32 s13, 0x2c00000
	s_mov_b32 s14, 0
	s_branch .Ltq1_c1024_1024

; __device__ __forceinline__ void phase0(const Params& P, unsigned char* smem) {
;     ...
;     auto lookup = [&](int it, TItem& t, int& N) {
;         int r = it < total ? it : total - 1;
;         t.src = nullptr; t.dst = nullptr; t.K = 0; t.mode = 0; t.n0 = 0; N = 0;
; #pragma unroll
;         for (int i = 0; i < 11; ++i) {
;             const int cnt = (tw[i].K >> 6) * (tw[i].N >> 5);
;             if (r >= 0 && r < cnt) {
;                 const int nblk = tw[i].N >> 5, kb = r / nblk, nb = r - kb * nblk, k0 = kb * 64, n0 = nb * 32, tid = threadIdx.x & 255;
;                 N = tw[i].N; t.K = tw[i].K; t.mode = tw[i].mode; t.n0 = n0;
;                 t.src = P.in[tw[i].in] + (size_t)(k0 + (tid >> 5)) * tw[i].N + n0 + (tid & 31);
;                 t.dst = (bf16_t*)(P.ws + tw[i].off) + k0 + (tid & 7) * 8;
;             }
;             r -= cnt;
;         }
;     };
;     {
;         const int stride = gridDim.x * 2;
;         int it = blockIdx.x * 2 + hb;
;         TItem cur, nxt; int Nc = 0, Nn = 0; float vn[8];
;         if (blockIdx.x * 2 < total) { lookup(it, nxt, Nn); transpose_load(nxt, Nn, vn); }
;         for (int base = blockIdx.x * 2; base < total; base += stride) {
;             float v[8];
; #pragma unroll
;             for (int i = 0; i < 8; ++i) v[i] = vn[i];
;             cur = nxt; Nc = Nn;
;             if (base + stride < total) { lookup(it + stride, nxt, Nn); transpose_load(nxt, Nn, vn); }
;             transpose_store(cur, v, scr);
;             it += stride;
;         }
.Ltq_le1:
	s_add_u32 s1, s1, 0x540
	s_cmpk_lt_u32 s1, 0x1310
	s_cbranch_scc0 .Ltq_last0f
	s_movk_i32 s19, 0x1600
	s_cmpk_lt_u32 s1, 0x580
	s_cselect_b32 s19, 0xb00, s19
	s_add_u32 s19, s19, s1
	s_cmpk_lt_u32 s19, 0x580
	s_cbranch_scc1 .Ltq2_m0
	s_cmpk_lt_u32 s19, 0xb00
	s_cbranch_scc1 .Ltq2_m1
	s_cmpk_lt_u32 s19, 0x1080
	s_cbranch_scc1 .Ltq2_m2
	s_cmpk_lt_u32 s19, 0x1600
	s_cbranch_scc1 .Ltq2_m3
	s_cmpk_lt_u32 s19, 0x1b80
	s_cbranch_scc1 .Ltq2_m4
	s_cmpk_lt_u32 s19, 0x2100
	s_cbranch_scc1 .Ltq2_m5
	s_cmpk_lt_u32 s19, 0x2910
	s_cbranch_scc1 .Ltq2_m6
	s_cmpk_lt_u32 s19, 0x2990
	s_cbranch_scc1 .Ltq2_m7
	s_cmpk_lt_u32 s19, 0x2a90
	s_cbranch_scc1 .Ltq2_m8
	s_cmpk_lt_u32 s19, 0x2b90
	s_cbranch_scc1 .Ltq2_m9
	s_sub_u32 s3, s19, 0x2b90
	v_readlane_b32 s6, v251, 43
	v_readlane_b32 s7, v251, 44
	s_mov_b32 s13, 0x2c00000
	s_mov_b32 s14, 0
	s_branch .Ltq2_c1024_1024

; __device__ __forceinline__ void phase0(const Params& P, unsigned char* smem) {
;     ...
;     auto lookup = [&](int it, TItem& t, int& N) {
;         int r = it < total ? it : total - 1;
;         t.src = nullptr; t.dst = nullptr; t.K = 0; t.mode = 0; t.n0 = 0; N = 0;
; #pragma unroll
;         for (int i = 0; i < 11; ++i) {
;             const int cnt = (tw[i].K >> 6) * (tw[i].N >> 5);
;             if (r >= 0 && r < cnt) {
;                 const int nblk = tw[i].N >> 5, kb = r / nblk, nb = r - kb * nblk, k0 = kb * 64, n0 = nb * 32, tid = threadIdx.x & 255;
;                 N = tw[i].N; t.K = tw[i].K; t.mode = tw[i].mode; t.n0 = n0;
;                 t.src = P.in[tw[i].in] + (size_t)(k0 + (tid >> 5)) * tw[i].N + n0 + (tid & 31);
;                 t.dst = (bf16_t*)(P.ws + tw[i].off) + k0 + (tid & 7) * 8;
;             }
;             r -= cnt;
;         }
;     };
;     {
;         const int stride = gridDim.x * 2;
;         int it = blockIdx.x * 2 + hb;
;         TItem cur, nxt; int Nc = 0, Nn = 0; float vn[8];
;         if (blockIdx.x * 2 < total) { lookup(it, nxt, Nn); transpose_load(nxt, Nn, vn); }
;         for (int base = blockIdx.x * 2; base < total; base += stride) {
;             float v[8];
; #pragma unroll
;             for (int i = 0; i < 8; ++i) v[i] = vn[i];
;             cur = nxt; Nc = Nn;
;             if (base + stride < total) { lookup(it + stride, nxt, Nn); transpose_load(nxt, Nn, vn); }
;             transpose_store(cur, v, scr);
;             it += stride;
;         }
.Ltq_pe1:
.Ltq_loop:
	s_add_u32 s1, s1, 0x540
	s_cmpk_lt_u32 s1, 0x1310
	s_cbranch_scc0 .Ltq_last1
	s_movk_i32 s19, 0x1600
	s_cmpk_lt_u32 s1, 0x580
	s_cselect_b32 s19, 0xb00, s19
	s_add_u32 s19, s19, s1
	s_cmpk_lt_u32 s19, 0x580
	s_cbranch_scc1 .Ltq3_m0
	s_cmpk_lt_u32 s19, 0xb00
	s_cbranch_scc1 .Ltq3_m1
	s_cmpk_lt_u32 s19, 0x1080
	s_cbranch_scc1 .Ltq3_m2
	s_cmpk_lt_u32 s19, 0x1600
	s_cbranch_scc1 .Ltq3_m3
	s_cmpk_lt_u32 s19, 0x1b80
	s_cbranch_scc1 .Ltq3_m4
	s_cmpk_lt_u32 s19, 0x2100
	s_cbranch_scc1 .Ltq3_m5
	s_cmpk_lt_u32 s19, 0x2910
	s_cbranch_scc1 .Ltq3_m6
	s_cmpk_lt_u32 s19, 0x2990
	s_cbranch_scc1 .Ltq3_m7
	s_cmpk_lt_u32 s19, 0x2a90
	s_cbranch_scc1 .Ltq3_m8
	s_cmpk_lt_u32 s19, 0x2b90
	s_cbranch_scc1 .Ltq3_m9
	s_sub_u32 s3, s19, 0x2b90
	v_readlane_b32 s6, v251, 43
	v_readlane_b32 s7, v251, 44
	s_mov_b32 s13, 0x2c00000
	s_mov_b32 s14, 0
	s_branch .Ltq3_c1024_1024

; __device__ __forceinline__ void phase4(const Params& P) {
;     ...
;     auto kf_val = [&](int e) -> float {
;         const int k = e & 511, n = (e >> 9) & 511, g = e >> 18;
;         const int t = n >> 4, c = n & 15, s = k >> 4, cp = k & 15;
;         const int d0 = t - s, d1 = s - t;
;         const float a0 = KD[(((0 * 32 + g) * 32 + (d0 > 0 ? d0 : 0)) * 16 + c) * 16 + cp];
;         const float a1 = KD[(((1 * 32 + g) * 32 + (d1 > 0 ? d1 : 0)) * 16 + c) * 16 + cp];
.Ltq_pe5:
.Ltq_done:
	s_nop 0
	s_nop 0
	s_nop 0
	s_nop 0
	s_nop 0
	s_nop 0
	s_nop 0
	s_nop 0
	s_nop 0
	s_nop 0
	s_nop 0
	s_nop 0
	s_nop 0
	s_nop 0
	s_nop 0
	v_lshrrev_b32_e32 v0, 1, v170
	v_and_b32_e32 v1, 1, v170
	v_lshlrev_b32_e32 v2, 4, v170
	v_lshlrev_b32_e32 v1, 5, v1
	v_readfirstlane_b32 s0, v171
	s_nop 3
	s_sub_u32 s1, s33, 88
	s_lshl_b32 s1, s1, 3
	s_add_u32 s0, s0, s1

; __device__ __forceinline__ void phase0(const Params& P, unsigned char* smem) {
;     ...
;     auto lookup = [&](int it, TItem& t, int& N) {
;         int r = it < total ? it : total - 1;
;         t.src = nullptr; t.dst = nullptr; t.K = 0; t.mode = 0; t.n0 = 0; N = 0;
; #pragma unroll
;         for (int i = 0; i < 11; ++i) {
;             const int cnt = (tw[i].K >> 6) * (tw[i].N >> 5);
;             if (r >= 0 && r < cnt) {
;                 const int nblk = tw[i].N >> 5, kb = r / nblk, nb = r - kb * nblk, k0 = kb * 64, n0 = nb * 32, tid = threadIdx.x & 255;
;                 N = tw[i].N; t.K = tw[i].K; t.mode = tw[i].mode; t.n0 = n0;
;                 t.src = P.in[tw[i].in] + (size_t)(k0 + (tid >> 5)) * tw[i].N + n0 + (tid & 31);
;                 t.dst = (bf16_t*)(P.ws + tw[i].off) + k0 + (tid & 7) * 8;
;             }
;             r -= cnt;
;         }
;     };
;     {
;         const int stride = gridDim.x * 2;
;         int it = blockIdx.x * 2 + hb;
;         TItem cur, nxt; int Nc = 0, Nn = 0; float vn[8];
;         if (blockIdx.x * 2 < total) { lookup(it, nxt, Nn); transpose_load(nxt, Nn, vn); }
;         for (int base = blockIdx.x * 2; base < total; base += stride) {
;             float v[8];
; #pragma unroll
;             for (int i = 0; i < 8; ++i) v[i] = vn[i];
;             cur = nxt; Nc = Nn;
;             if (base + stride < total) { lookup(it + stride, nxt, Nn); transpose_load(nxt, Nn, vn); }
;             transpose_store(cur, v, scr);
;             it += stride;
;         }
;     }
.Lbwb_end:
	s_mov_b64 exec, -1
	v_and_b32_e32 v1, 63, v168
	v_lshrrev_b32_e32 v14, 6, v168
	s_nop 1
	v_readfirstlane_b32 s0, v14
	s_nop 3
	v_lshrrev_b32_e32 v2, 3, v1
	v_and_b32_e32 v3, 7, v1
	v_lshrrev_b32_e32 v4, 2, v2
	v_and_b32_e32 v14, 3, v2
	v_lshl_or_b32 v4, v4, 3, v14
	s_mulk_i32 s0, 0x2100
	s_add_u32 s3, s0, 16
	v_mul_u32_u24_e32 v5, 0x84, v2
	v_lshl_add_u32 v5, v3, 4, v5
	v_add_u32_e32 v5, s3, v5
	v_add_u32_e32 v6, 0x420, v5
	v_add_u32_e32 v7, 0x420, v6
	v_add_u32_e32 v8, 0x420, v7
	v_add_u32_e32 v9, 0x420, v8
	v_add_u32_e32 v10, 0x420, v9
	v_add_u32_e32 v11, 0x420, v10
	v_add_u32_e32 v12, 0x420, v11
	v_mul_u32_u24_e32 v13, 0x420, v3
	v_lshl_add_u32 v13, v2, 2, v13
	v_add_u32_e32 v13, s3, v13
	v_lshlrev_b32_e32 v3, 4, v3
	v_lshrrev_b32_e32 v14, 6, v168
	s_nop 1
	v_readfirstlane_b32 s0, v14
	s_nop 3
	s_sub_u32 s4, s33, 196
	s_lshl_b32 s4, s4, 3
	s_add_u32 s0, s0, s4
	s_mov_b32 s1, s0
	s_add_u32 s19, s1, 0x2910
	s_cmpk_lt_u32 s19, 0x580
	s_cbranch_scc1 .Ltu1_m0
	s_cmpk_lt_u32 s19, 0xb00
	s_cbranch_scc1 .Ltu1_m1
	s_cmpk_lt_u32 s19, 0x1080
	s_cbranch_scc1 .Ltu1_m2
	s_cmpk_lt_u32 s19, 0x1600
	s_cbranch_scc1 .Ltu1_m3
	s_cmpk_lt_u32 s19, 0x1b80
	s_cbranch_scc1 .Ltu1_m4
	s_cmpk_lt_u32 s19, 0x2100
	s_cbranch_scc1 .Ltu1_m5
	s_cmpk_lt_u32 s19, 0x2910
	s_cbranch_scc1 .Ltu1_m6
	s_cmpk_lt_u32 s19, 0x2990
	s_cbranch_scc1 .Ltu1_m7
	s_cmpk_lt_u32 s19, 0x2a90
	s_cbranch_scc1 .Ltu1_m8
	s_cmpk_lt_u32 s19, 0x2b90
	s_cbranch_scc1 .Ltu1_m9
	s_sub_u32 s3, s19, 0x2b90
	v_readlane_b32 s6, v251, 43
	v_readlane_b32 s7, v251, 44
	s_mov_b32 s13, 0x2c00000
	s_mov_b32 s14, 0
	s_branch .Ltu1_c1024_1024

; __device__ __forceinline__ void phase0(const Params& P, unsigned char* smem) {
;     ...
;     auto lookup = [&](int it, TItem& t, int& N) {
;         int r = it < total ? it : total - 1;
;         t.src = nullptr; t.dst = nullptr; t.K = 0; t.mode = 0; t.n0 = 0; N = 0;
; #pragma unroll
;         for (int i = 0; i < 11; ++i) {
;             const int cnt = (tw[i].K >> 6) * (tw[i].N >> 5);
;             if (r >= 0 && r < cnt) {
;                 const int nblk = tw[i].N >> 5, kb = r / nblk, nb = r - kb * nblk, k0 = kb * 64, n0 = nb * 32, tid = threadIdx.x & 255;
;                 N = tw[i].N; t.K = tw[i].K; t.mode = tw[i].mode; t.n0 = n0;
;                 t.src = P.in[tw[i].in] + (size_t)(k0 + (tid >> 5)) * tw[i].N + n0 + (tid & 31);
;                 t.dst = (bf16_t*)(P.ws + tw[i].off) + k0 + (tid & 7) * 8;
;             }
;             r -= cnt;
;         }
;     };
;     {
;         const int stride = gridDim.x * 2;
;         int it = blockIdx.x * 2 + hb;
;         TItem cur, nxt; int Nc = 0, Nn = 0; float vn[8];
;         if (blockIdx.x * 2 < total) { lookup(it, nxt, Nn); transpose_load(nxt, Nn, vn); }
;         for (int base = blockIdx.x * 2; base < total; base += stride) {
;             float v[8];
; #pragma unroll
;             for (int i = 0; i < 8; ++i) v[i] = vn[i];
;             cur = nxt; Nc = Nn;
;             if (base + stride < total) { lookup(it + stride, nxt, Nn); transpose_load(nxt, Nn, vn); }
;             transpose_store(cur, v, scr);
;             it += stride;
;         }
.Ltu_le1:
	s_add_u32 s1, s1, 0x1e0
	s_cmpk_lt_u32 s1, 0x480
	s_cbranch_scc0 .Ltu_last0f
	s_add_u32 s19, s1, 0x2910
	s_cmpk_lt_u32 s19, 0x580
	s_cbranch_scc1 .Ltu2_m0
	s_cmpk_lt_u32 s19, 0xb00
	s_cbranch_scc1 .Ltu2_m1
	s_cmpk_lt_u32 s19, 0x1080
	s_cbranch_scc1 .Ltu2_m2
	s_cmpk_lt_u32 s19, 0x1600
	s_cbranch_scc1 .Ltu2_m3
	s_cmpk_lt_u32 s19, 0x1b80
	s_cbranch_scc1 .Ltu2_m4
	s_cmpk_lt_u32 s19, 0x2100
	s_cbranch_scc1 .Ltu2_m5
	s_cmpk_lt_u32 s19, 0x2910
	s_cbranch_scc1 .Ltu2_m6
	s_cmpk_lt_u32 s19, 0x2990
	s_cbranch_scc1 .Ltu2_m7
	s_cmpk_lt_u32 s19, 0x2a90
	s_cbranch_scc1 .Ltu2_m8
	s_cmpk_lt_u32 s19, 0x2b90
	s_cbranch_scc1 .Ltu2_m9
	s_sub_u32 s3, s19, 0x2b90
	v_readlane_b32 s6, v251, 43
	v_readlane_b32 s7, v251, 44
	s_mov_b32 s13, 0x2c00000
	s_mov_b32 s14, 0
	s_branch .Ltu2_c1024_1024

; __device__ __forceinline__ void phase0(const Params& P, unsigned char* smem) {
;     ...
;     auto lookup = [&](int it, TItem& t, int& N) {
;         int r = it < total ? it : total - 1;
;         t.src = nullptr; t.dst = nullptr; t.K = 0; t.mode = 0; t.n0 = 0; N = 0;
; #pragma unroll
;         for (int i = 0; i < 11; ++i) {
;             const int cnt = (tw[i].K >> 6) * (tw[i].N >> 5);
;             if (r >= 0 && r < cnt) {
;                 const int nblk = tw[i].N >> 5, kb = r / nblk, nb = r - kb * nblk, k0 = kb * 64, n0 = nb * 32, tid = threadIdx.x & 255;
;                 N = tw[i].N; t.K = tw[i].K; t.mode = tw[i].mode; t.n0 = n0;
;                 t.src = P.in[tw[i].in] + (size_t)(k0 + (tid >> 5)) * tw[i].N + n0 + (tid & 31);
;                 t.dst = (bf16_t*)(P.ws + tw[i].off) + k0 + (tid & 7) * 8;
;             }
;             r -= cnt;
;         }
;     };
;     {
;         const int stride = gridDim.x * 2;
;         int it = blockIdx.x * 2 + hb;
;         TItem cur, nxt; int Nc = 0, Nn = 0; float vn[8];
;         if (blockIdx.x * 2 < total) { lookup(it, nxt, Nn); transpose_load(nxt, Nn, vn); }
;         for (int base = blockIdx.x * 2; base < total; base += stride) {
;             float v[8];
; #pragma unroll
;             for (int i = 0; i < 8; ++i) v[i] = vn[i];
;             cur = nxt; Nc = Nn;
;             if (base + stride < total) { lookup(it + stride, nxt, Nn); transpose_load(nxt, Nn, vn); }
;             transpose_store(cur, v, scr);
;             it += stride;
;         }
.Ltu_pe1:
.Ltu_loop:
	s_add_u32 s1, s1, 0x1e0
	s_cmpk_lt_u32 s1, 0x480
	s_cbranch_scc0 .Ltu_last1
	s_add_u32 s19, s1, 0x2910
	s_cmpk_lt_u32 s19, 0x580
	s_cbranch_scc1 .Ltu3_m0
	s_cmpk_lt_u32 s19, 0xb00
	s_cbranch_scc1 .Ltu3_m1
	s_cmpk_lt_u32 s19, 0x1080
	s_cbranch_scc1 .Ltu3_m2
	s_cmpk_lt_u32 s19, 0x1600
	s_cbranch_scc1 .Ltu3_m3
	s_cmpk_lt_u32 s19, 0x1b80
	s_cbranch_scc1 .Ltu3_m4
	s_cmpk_lt_u32 s19, 0x2100
	s_cbranch_scc1 .Ltu3_m5
	s_cmpk_lt_u32 s19, 0x2910
	s_cbranch_scc1 .Ltu3_m6
	s_cmpk_lt_u32 s19, 0x2990
	s_cbranch_scc1 .Ltu3_m7
	s_cmpk_lt_u32 s19, 0x2a90
	s_cbranch_scc1 .Ltu3_m8
	s_cmpk_lt_u32 s19, 0x2b90
	s_cbranch_scc1 .Ltu3_m9
	s_sub_u32 s3, s19, 0x2b90
	v_readlane_b32 s6, v251, 43
	v_readlane_b32 s7, v251, 44
	s_mov_b32 s13, 0x2c00000
	s_mov_b32 s14, 0
	s_branch .Ltu3_c1024_1024

.Ltu_skip:
	s_nop 0
	s_nop 0
	s_nop 0
	s_nop 0
	s_nop 0
	s_nop 0
	s_nop 0
	s_nop 0
	s_nop 0
	s_nop 0
	s_nop 0
	s_nop 0
	s_nop 0
	s_nop 0
